# FOXIN: row sum-of-squares and q/k gains staged once per workgroup in LDS tables; epilogues read them by ds_read (no vmcnt wait behind the next unit's prefetch DMAs); plus HG3 og hoist
# speedup vs baseline: 1.0006x; 1.0006x over previous
.LBB0_123:
	s_cmp_lt_i32 s30, 2
	s_cselect_b64 s[8:9], -1, 0
	s_add_u32 s2, s28, 0x4a0000
	s_addc_u32 s3, s29, 0
	v_writelane_b32 v254, s2, 14
	s_and_b64 s[0:1], s[8:9], s[0:1]
	s_andn2_b64 vcc, exec, s[0:1]
	v_writelane_b32 v254, s3, 15
	v_writelane_b32 v254, s97, 16
	s_cbranch_vccnz .LBB0_295
	v_mbcnt_lo_u32_b32 v232, -1, 0
	v_mbcnt_hi_u32_b32 v232, -1, v232
	s_lshr_b32 s98, s33, 6
	s_and_b32 s99, s16, 7
	s_lshl_b32 s99, s99, 3
	s_bfe_u32 s100, s16, 0x30003
	s_add_i32 s99, s99, s100
	s_lshl_b32 s99, s99, 8
	s_lshl_b32 s100, s98, 5
	s_add_i32 s99, s99, s100
	v_and_b32_e32 v233, 15, v232
	v_lshrrev_b32_e32 v234, 4, v232
	v_add_u32_e32 v235, s99, v233
	v_lshlrev_b32_e32 v236, 6, v235
	v_lshl_add_u32 v236, v234, 4, v236
	s_add_u32 s100, s28, 0x100000
	s_addc_u32 s101, s29, 0
	global_load_dwordx4 v[240:243], v236, s[100:101]
	global_load_dwordx4 v[244:247], v236, s[100:101] offset:1024
	v_lshlrev_b32_e32 v237, 2, v232
	global_load_dword v248, v237, s[62:63]
	global_load_dword v249, v237, s[64:65]
	v_xor_b32_e32 v238, 16, v232
	v_lshlrev_b32_e32 v238, 2, v238
	v_xor_b32_e32 v239, 32, v232
	v_lshlrev_b32_e32 v239, 2, v239
	s_waitcnt vmcnt(0)
	v_add_f32_e32 v240, v241, v240
	v_add_f32_e32 v241, v242, v243
	v_add_f32_e32 v244, v245, v244
	v_add_f32_e32 v245, v246, v247
	v_add_f32_e32 v242, v244, v245
	v_add_f32_e32 v243, v240, v241
	ds_bpermute_b32 v247, v238, v243
	ds_bpermute_b32 v246, v238, v242
	s_waitcnt lgkmcnt(0)
	v_pk_add_f32 v[250:251], v[242:243], v[246:247]
	ds_bpermute_b32 v253, v239, v251
	ds_bpermute_b32 v252, v239, v250
	s_waitcnt lgkmcnt(0)
	v_pk_add_f32 v[250:251], v[250:251], v[252:253]
	s_lshl_b32 s99, s98, 7
	v_lshl_add_u32 v236, v233, 2, s99
	v_add_u32_e32 v236, 0x22800, v236
	ds_write_b32 v236, v251
	ds_write_b32 v236, v250 offset:64
	v_add_u32_e32 v237, 0x22c00, v237
	ds_write_b32 v237, v248
	ds_write_b32 v237, v249 offset:256
	s_waitcnt lgkmcnt(0)
	v_mbcnt_lo_u32_b32 v26, -1, 0
	v_mbcnt_hi_u32_b32 v26, -1, v26
	s_cmpk_lt_i32 s16, 0x400
	v_add_u32_e32 v0, s33, v26
	s_cselect_b64 s[4:5], -1, 0
	s_cmpk_gt_i32 s16, 0x3ff
	v_readfirstlane_b32 s10, v0
	s_cbranch_scc1 .LBB0_127
	s_ashr_i32 s0, s16, 31
	s_lshr_b32 s0, s0, 29
	s_add_i32 s2, s16, s0
	s_and_b32 s0, s2, -8
	s_sub_i32 s3, s16, s0
	s_cmp_gt_i32 s3, -1
	s_cbranch_scc0 .LBB0_128
	s_lshl_b32 s6, s3, 7
	s_cbranch_execz .LBB0_129
	s_branch .LBB0_130

.LBB0_153:
	v_and_b32_e32 v49, 64, v217
	v_xor_b32_e32 v48, 16, v217
	v_add_u32_e32 v49, 64, v49
	v_cmp_lt_i32_e32 vcc, v48, v49
	s_lshl_b32 s81, s86, 8
	s_add_i32 s81, s81, s95
	v_cndmask_b32_e32 v48, v217, v48, vcc
	v_lshlrev_b32_e32 v220, 2, v48
	v_xor_b32_e32 v48, 32, v217
	v_or_b32_e32 v194, s81, v153
	v_cmp_lt_i32_e32 vcc, v48, v49
	v_ashrrev_i32_e32 v195, 31, v194
	v_or_b32_e32 v188, 16, v194
	v_cndmask_b32_e32 v48, v217, v48, vcc
	v_lshlrev_b32_e32 v221, 2, v48
	v_ashrrev_i32_e32 v189, 31, v188
	v_or_b32_e32 v186, 32, v194
	v_ashrrev_i32_e32 v187, 31, v186
	v_or_b32_e32 v180, 48, v194
	v_ashrrev_i32_e32 v181, 31, v180
	v_add_u32_e32 v178, 0x80, v194
	v_ashrrev_i32_e32 v179, 31, v178
	v_add_u32_e32 v172, 0x90, v194
	v_ashrrev_i32_e32 v173, 31, v172
	v_add_u32_e32 v170, 0xa0, v194
	v_ashrrev_i32_e32 v171, 31, v170
	v_add_u32_e32 v168, 0xb0, v194
	v_ashrrev_i32_e32 v169, 31, v168
	s_ashr_i32 s79, s92, 2
	s_cmp_gt_i32 s79, 1
	s_cselect_b64 s[8:9], -1, 0
	s_and_b64 vcc, exec, s[8:9]
	v_and_b32_e32 v48, 0xff, v194
	v_lshlrev_b32_e32 v48, 2, v48
	v_add_u32_e32 v48, 0x22800, v48
	ds_read_b32 v197, v48
	ds_read_b32 v196, v48 offset:64
	ds_read_b32 v191, v48 offset:128
	ds_read_b32 v190, v48 offset:192
	ds_read_b32 v183, v48 offset:512
	ds_read_b32 v182, v48 offset:576
	ds_read_b32 v175, v48 offset:640
	ds_read_b32 v174, v48 offset:704
	v_mov_b32_e32 v198, 0
	v_mov_b32_e32 v199, 0
	v_mov_b32_e32 v192, 0
	v_mov_b32_e32 v193, 0
	v_mov_b32_e32 v184, 0
	v_mov_b32_e32 v185, 0
	v_mov_b32_e32 v176, 0
	v_mov_b32_e32 v177, 0
	s_waitcnt lgkmcnt(0)
	s_cbranch_vccnz .LBB0_155
	s_cmp_lt_u32 s92, 4
	s_cselect_b32 s2, 0, 0x100
	s_add_i32 s2, s2, 0x22c00
	v_add_u32_e32 v232, s2, v218
	ds_read_b128 v[56:59], v232
	ds_read_b128 v[48:51], v232 offset:16
	ds_read_b128 v[60:63], v232 offset:128
	ds_read_b128 v[52:55], v232 offset:144
	s_waitcnt lgkmcnt(0)

.LBB0_159:
	s_andn2_b64 vcc, exec, s[86:87]
	v_cndmask_b32_e64 v197, 1.0, v219, s[4:5]
	s_cbranch_vccnz .LBB0_161
	v_pk_mul_f32 v[130:131], v[198:199], v[198:199]
	v_pk_mul_f32 v[132:133], v[200:201], v[200:201]
	v_add_f32_e32 v130, v130, v131
	v_add_f32_e32 v130, v132, v130
	v_pk_mul_f32 v[134:135], v[202:203], v[202:203]
	v_add_f32_e32 v130, v133, v130
	v_add_f32_e32 v130, v134, v130
	v_pk_mul_f32 v[136:137], v[206:207], v[206:207]
	v_add_f32_e32 v130, v135, v130
	v_add_f32_e32 v130, v136, v130
	v_pk_mul_f32 v[138:139], v[204:205], v[204:205]
	v_add_f32_e32 v130, v137, v130
	v_add_f32_e32 v130, v138, v130
	v_pk_mul_f32 v[140:141], v[208:209], v[208:209]
	v_add_f32_e32 v130, v139, v130
	v_add_f32_e32 v130, v140, v130
	v_pk_mul_f32 v[142:143], v[128:129], v[128:129]
	v_add_f32_e32 v130, v141, v130
	v_add_f32_e32 v130, v142, v130
	v_pk_mul_f32 v[212:213], v[210:211], v[210:211]
	v_add_f32_e32 v130, v143, v130
	v_add_f32_e32 v130, v212, v130
	v_add_f32_e32 v130, v213, v130
	ds_bpermute_b32 v131, v220, v130
	s_waitcnt lgkmcnt(0)
	v_add_f32_e32 v130, v130, v131
	ds_bpermute_b32 v131, v221, v130
	s_waitcnt lgkmcnt(0)
	v_add_f32_e32 v130, v130, v131
	v_fmamk_f32 v130, v130, 0x3c800000, v166
	v_mul_f32_e32 v131, 0x4b800000, v130
	v_cmp_gt_f32_e32 vcc, s12, v130
	s_nop 1
	v_cndmask_b32_e32 v130, v130, v131, vcc
	v_rsq_f32_e32 v130, v130
	s_nop 0
	v_mul_f32_e32 v131, 0x45800000, v130
	v_cndmask_b32_e32 v130, v130, v131, vcc
	v_mul_f32_e32 v154, v197, v130
	s_nop 0
	v_pk_mul_f32 v[134:135], v[48:49], v[154:155] op_sel_hi:[1,0]
	s_nop 0
	v_pk_mul_f32 v[142:143], v[52:53], v[154:155] op_sel_hi:[1,0]
	v_pk_mul_f32 v[136:137], v[202:203], v[134:135]
	v_pk_mul_f32 v[134:135], v[50:51], v[154:155] op_sel_hi:[1,0]
	v_pk_mul_f32 v[130:131], v[56:57], v[154:155] op_sel_hi:[1,0]
	v_pk_mul_f32 v[132:133], v[58:59], v[154:155] op_sel_hi:[1,0]
	v_pk_mul_f32 v[140:141], v[206:207], v[134:135]
	s_nop 0
	v_pk_mul_f32 v[134:135], v[60:61], v[154:155] op_sel_hi:[1,0]
	v_pk_mul_f32 v[138:139], v[62:63], v[154:155] op_sel_hi:[1,0]
	v_pk_mul_f32 v[142:143], v[128:129], v[142:143]
	v_pk_mul_f32 v[128:129], v[54:55], v[154:155] op_sel_hi:[1,0]
	v_pk_mul_f32 v[130:131], v[198:199], v[130:131]
	v_pk_mul_f32 v[132:133], v[200:201], v[132:133]
	v_pk_mul_f32 v[134:135], v[204:205], v[134:135]
	v_pk_mul_f32 v[138:139], v[208:209], v[138:139]
	v_pk_mul_f32 v[212:213], v[210:211], v[128:129]

.LBB0_187:
	v_pk_mul_f32 v[114:115], v[130:131], v[130:131]
	v_pk_mul_f32 v[116:117], v[132:133], v[132:133]
	v_add_f32_e32 v114, v114, v115
	v_add_f32_e32 v114, v116, v114
	v_pk_mul_f32 v[118:119], v[134:135], v[134:135]
	v_add_f32_e32 v114, v117, v114
	v_add_f32_e32 v114, v118, v114
	v_pk_mul_f32 v[120:121], v[138:139], v[138:139]
	v_add_f32_e32 v114, v119, v114
	v_add_f32_e32 v114, v120, v114
	v_pk_mul_f32 v[122:123], v[136:137], v[136:137]
	v_add_f32_e32 v114, v121, v114
	v_add_f32_e32 v114, v122, v114
	v_pk_mul_f32 v[124:125], v[140:141], v[140:141]
	v_add_f32_e32 v114, v123, v114
	v_add_f32_e32 v114, v124, v114
	v_pk_mul_f32 v[126:127], v[112:113], v[112:113]
	v_add_f32_e32 v114, v125, v114
	v_add_f32_e32 v114, v126, v114
	v_pk_mul_f32 v[194:195], v[142:143], v[142:143]
	v_add_f32_e32 v114, v127, v114
	v_add_f32_e32 v114, v194, v114
	v_add_f32_e32 v114, v195, v114
	ds_bpermute_b32 v115, v220, v114
	s_waitcnt lgkmcnt(0)
	v_add_f32_e32 v114, v114, v115
	ds_bpermute_b32 v115, v221, v114
	s_waitcnt lgkmcnt(0)
	v_add_f32_e32 v114, v114, v115
	v_fmamk_f32 v114, v114, 0x3c800000, v166
	v_mul_f32_e32 v115, 0x4b800000, v114
	v_cmp_gt_f32_e32 vcc, s12, v114
	s_nop 1
	v_cndmask_b32_e32 v114, v114, v115, vcc
	v_rsq_f32_e32 v114, v114
	s_nop 0
	v_mul_f32_e32 v115, 0x45800000, v114
	v_cndmask_b32_e32 v114, v114, v115, vcc
	v_mul_f32_e32 v154, v197, v114
	s_nop 0
	v_pk_mul_f32 v[118:119], v[48:49], v[154:155] op_sel_hi:[1,0]
	s_nop 0
	v_pk_mul_f32 v[126:127], v[52:53], v[154:155] op_sel_hi:[1,0]
	v_pk_mul_f32 v[120:121], v[134:135], v[118:119]
	v_pk_mul_f32 v[118:119], v[50:51], v[154:155] op_sel_hi:[1,0]
	v_pk_mul_f32 v[114:115], v[56:57], v[154:155] op_sel_hi:[1,0]
	v_pk_mul_f32 v[116:117], v[58:59], v[154:155] op_sel_hi:[1,0]
	v_pk_mul_f32 v[124:125], v[138:139], v[118:119]
	s_nop 0
	v_pk_mul_f32 v[118:119], v[60:61], v[154:155] op_sel_hi:[1,0]
	v_pk_mul_f32 v[122:123], v[62:63], v[154:155] op_sel_hi:[1,0]
	v_pk_mul_f32 v[126:127], v[112:113], v[126:127]
	v_pk_mul_f32 v[112:113], v[54:55], v[154:155] op_sel_hi:[1,0]
	v_pk_mul_f32 v[114:115], v[130:131], v[114:115]
	v_pk_mul_f32 v[116:117], v[132:133], v[116:117]
	v_pk_mul_f32 v[118:119], v[136:137], v[118:119]
	v_pk_mul_f32 v[122:123], v[140:141], v[122:123]
	v_pk_mul_f32 v[194:195], v[142:143], v[112:113]
	s_and_b64 vcc, exec, s[4:5]
	s_cbranch_vccz .LBB0_175

.LBB0_204:
	v_pk_mul_f32 v[96:97], v[108:109], v[108:109]
	v_pk_mul_f32 v[98:99], v[114:115], v[114:115]
	v_add_f32_e32 v96, v96, v97
	v_add_f32_e32 v96, v98, v96
	v_pk_mul_f32 v[100:101], v[116:117], v[116:117]
	v_add_f32_e32 v96, v99, v96
	v_add_f32_e32 v96, v100, v96
	v_pk_mul_f32 v[102:103], v[122:123], v[122:123]
	v_add_f32_e32 v96, v101, v96
	v_add_f32_e32 v96, v102, v96
	v_pk_mul_f32 v[104:105], v[118:119], v[118:119]
	v_add_f32_e32 v96, v103, v96
	v_add_f32_e32 v96, v104, v96
	v_pk_mul_f32 v[106:107], v[124:125], v[124:125]
	v_add_f32_e32 v96, v105, v96
	v_add_f32_e32 v96, v106, v96
	v_pk_mul_f32 v[110:111], v[120:121], v[120:121]
	v_add_f32_e32 v96, v107, v96
	v_add_f32_e32 v96, v110, v96
	v_pk_mul_f32 v[130:131], v[126:127], v[126:127]
	v_add_f32_e32 v96, v111, v96
	v_add_f32_e32 v96, v130, v96
	v_add_f32_e32 v96, v131, v96
	ds_bpermute_b32 v97, v220, v96
	s_waitcnt lgkmcnt(0)
	v_add_f32_e32 v96, v96, v97
	ds_bpermute_b32 v97, v221, v96
	s_waitcnt lgkmcnt(0)
	v_add_f32_e32 v96, v96, v97
	v_fmamk_f32 v96, v96, 0x3c800000, v166
	v_mul_f32_e32 v97, 0x4b800000, v96
	v_cmp_gt_f32_e32 vcc, s12, v96
	s_nop 1
	v_cndmask_b32_e32 v96, v96, v97, vcc
	v_rsq_f32_e32 v96, v96
	s_nop 0
	v_mul_f32_e32 v97, 0x45800000, v96
	v_cndmask_b32_e32 v96, v96, v97, vcc
	v_mul_f32_e32 v130, v197, v96
	s_nop 0
	v_pk_mul_f32 v[96:97], v[56:57], v[130:131] op_sel_hi:[1,0]
	v_pk_mul_f32 v[100:101], v[48:49], v[130:131] op_sel_hi:[1,0]
	v_pk_mul_f32 v[96:97], v[108:109], v[96:97]
	v_pk_mul_f32 v[102:103], v[116:117], v[100:101]
	v_pk_mul_f32 v[100:101], v[50:51], v[130:131] op_sel_hi:[1,0]
	s_nop 0
	v_pk_mul_f32 v[108:109], v[52:53], v[130:131] op_sel_hi:[1,0]
	v_pk_mul_f32 v[98:99], v[58:59], v[130:131] op_sel_hi:[1,0]
	v_pk_mul_f32 v[106:107], v[122:123], v[100:101]
	s_nop 0
	v_pk_mul_f32 v[100:101], v[60:61], v[130:131] op_sel_hi:[1,0]
	v_pk_mul_f32 v[104:105], v[62:63], v[130:131] op_sel_hi:[1,0]
	v_pk_mul_f32 v[110:111], v[120:121], v[108:109]
	v_pk_mul_f32 v[108:109], v[54:55], v[130:131] op_sel_hi:[1,0]
	v_pk_mul_f32 v[98:99], v[114:115], v[98:99]
	v_pk_mul_f32 v[100:101], v[118:119], v[100:101]
	v_pk_mul_f32 v[104:105], v[124:125], v[104:105]
	v_pk_mul_f32 v[130:131], v[126:127], v[108:109]
	s_and_b64 vcc, exec, s[4:5]
	s_cbranch_vccz .LBB0_192

.LBB0_221:
	v_pk_mul_f32 v[82:83], v[96:97], v[96:97]
	v_pk_mul_f32 v[84:85], v[98:99], v[98:99]
	v_add_f32_e32 v82, v82, v83
	v_add_f32_e32 v82, v84, v82
	v_pk_mul_f32 v[86:87], v[100:101], v[100:101]
	v_add_f32_e32 v82, v85, v82
	v_add_f32_e32 v82, v86, v82
	v_pk_mul_f32 v[88:89], v[104:105], v[104:105]
	v_add_f32_e32 v82, v87, v82
	v_add_f32_e32 v82, v88, v82
	v_pk_mul_f32 v[90:91], v[102:103], v[102:103]
	v_add_f32_e32 v82, v89, v82
	v_add_f32_e32 v82, v90, v82
	v_pk_mul_f32 v[92:93], v[106:107], v[106:107]
	v_add_f32_e32 v82, v91, v82
	v_add_f32_e32 v82, v92, v82
	v_pk_mul_f32 v[94:95], v[80:81], v[80:81]
	v_add_f32_e32 v82, v93, v82
	v_add_f32_e32 v82, v94, v82
	v_pk_mul_f32 v[110:111], v[108:109], v[108:109]
	v_add_f32_e32 v82, v95, v82
	v_add_f32_e32 v82, v110, v82
	v_add_f32_e32 v82, v111, v82
	ds_bpermute_b32 v83, v220, v82
	s_waitcnt lgkmcnt(0)
	v_add_f32_e32 v82, v82, v83
	ds_bpermute_b32 v83, v221, v82
	s_waitcnt lgkmcnt(0)
	v_add_f32_e32 v82, v82, v83
	v_fmamk_f32 v82, v82, 0x3c800000, v166
	v_mul_f32_e32 v83, 0x4b800000, v82
	v_cmp_gt_f32_e32 vcc, s12, v82
	s_nop 1
	v_cndmask_b32_e32 v82, v82, v83, vcc
	v_rsq_f32_e32 v82, v82
	s_nop 0
	v_mul_f32_e32 v83, 0x45800000, v82
	v_cndmask_b32_e32 v82, v82, v83, vcc
	v_mul_f32_e32 v110, v197, v82
	s_nop 0
	v_pk_mul_f32 v[86:87], v[48:49], v[110:111] op_sel_hi:[1,0]
	s_nop 0
	v_pk_mul_f32 v[94:95], v[52:53], v[110:111] op_sel_hi:[1,0]
	v_pk_mul_f32 v[88:89], v[100:101], v[86:87]
	v_pk_mul_f32 v[86:87], v[50:51], v[110:111] op_sel_hi:[1,0]
	v_pk_mul_f32 v[82:83], v[56:57], v[110:111] op_sel_hi:[1,0]
	v_pk_mul_f32 v[84:85], v[58:59], v[110:111] op_sel_hi:[1,0]
	v_pk_mul_f32 v[92:93], v[104:105], v[86:87]
	s_nop 0
	v_pk_mul_f32 v[86:87], v[60:61], v[110:111] op_sel_hi:[1,0]
	v_pk_mul_f32 v[90:91], v[62:63], v[110:111] op_sel_hi:[1,0]
	v_pk_mul_f32 v[94:95], v[80:81], v[94:95]
	v_pk_mul_f32 v[80:81], v[54:55], v[110:111] op_sel_hi:[1,0]
	v_pk_mul_f32 v[82:83], v[96:97], v[82:83]
	v_pk_mul_f32 v[84:85], v[98:99], v[84:85]
	v_pk_mul_f32 v[86:87], v[102:103], v[86:87]
	v_pk_mul_f32 v[90:91], v[106:107], v[90:91]
	v_pk_mul_f32 v[110:111], v[108:109], v[80:81]
	s_and_b64 vcc, exec, s[4:5]
	s_cbranch_vccz .LBB0_209

.LBB0_227:
	s_andn2_b64 vcc, exec, s[86:87]
	s_cbranch_vccnz .LBB0_229
	v_pk_mul_f32 v[66:67], v[82:83], v[82:83]
	v_pk_mul_f32 v[68:69], v[84:85], v[84:85]
	v_add_f32_e32 v66, v66, v67
	v_add_f32_e32 v66, v68, v66
	v_pk_mul_f32 v[70:71], v[86:87], v[86:87]
	v_add_f32_e32 v66, v69, v66
	v_add_f32_e32 v66, v70, v66
	v_pk_mul_f32 v[72:73], v[90:91], v[90:91]
	v_add_f32_e32 v66, v71, v66
	v_add_f32_e32 v66, v72, v66
	v_pk_mul_f32 v[74:75], v[88:89], v[88:89]
	v_add_f32_e32 v66, v73, v66
	v_add_f32_e32 v66, v74, v66
	v_pk_mul_f32 v[76:77], v[92:93], v[92:93]
	v_add_f32_e32 v66, v75, v66
	v_add_f32_e32 v66, v76, v66
	v_pk_mul_f32 v[78:79], v[64:65], v[64:65]
	v_add_f32_e32 v66, v77, v66
	v_add_f32_e32 v66, v78, v66
	v_pk_mul_f32 v[96:97], v[94:95], v[94:95]
	v_add_f32_e32 v66, v79, v66
	v_add_f32_e32 v66, v96, v66
	v_add_f32_e32 v66, v97, v66
	ds_bpermute_b32 v67, v220, v66
	s_waitcnt lgkmcnt(0)
	v_add_f32_e32 v66, v66, v67
	ds_bpermute_b32 v67, v221, v66
	s_waitcnt lgkmcnt(0)
	v_add_f32_e32 v66, v66, v67
	v_fmamk_f32 v66, v66, 0x3c800000, v166
	v_mul_f32_e32 v67, 0x4b800000, v66
	v_cmp_gt_f32_e32 vcc, s12, v66
	s_nop 1
	v_cndmask_b32_e32 v66, v66, v67, vcc
	v_rsq_f32_e32 v66, v66
	s_nop 0
	v_mul_f32_e32 v67, 0x45800000, v66
	v_cndmask_b32_e32 v66, v66, v67, vcc
	v_mul_f32_e32 v96, v197, v66
	s_nop 0
	v_pk_mul_f32 v[70:71], v[48:49], v[96:97] op_sel_hi:[1,0]
	s_nop 0
	v_pk_mul_f32 v[78:79], v[52:53], v[96:97] op_sel_hi:[1,0]
	v_pk_mul_f32 v[72:73], v[86:87], v[70:71]
	v_pk_mul_f32 v[70:71], v[50:51], v[96:97] op_sel_hi:[1,0]
	v_pk_mul_f32 v[66:67], v[56:57], v[96:97] op_sel_hi:[1,0]
	v_pk_mul_f32 v[68:69], v[58:59], v[96:97] op_sel_hi:[1,0]
	v_pk_mul_f32 v[76:77], v[90:91], v[70:71]
	s_nop 0
	v_pk_mul_f32 v[70:71], v[60:61], v[96:97] op_sel_hi:[1,0]
	v_pk_mul_f32 v[74:75], v[62:63], v[96:97] op_sel_hi:[1,0]
	v_pk_mul_f32 v[78:79], v[64:65], v[78:79]
	v_pk_mul_f32 v[64:65], v[54:55], v[96:97] op_sel_hi:[1,0]
	v_pk_mul_f32 v[66:67], v[82:83], v[66:67]
	v_pk_mul_f32 v[68:69], v[84:85], v[68:69]
	v_pk_mul_f32 v[70:71], v[88:89], v[70:71]
	v_pk_mul_f32 v[74:75], v[92:93], v[74:75]
	v_pk_mul_f32 v[96:97], v[94:95], v[64:65]

.LBB0_255:
	v_pk_mul_f32 v[34:35], v[66:67], v[66:67]
	v_pk_mul_f32 v[36:37], v[68:69], v[68:69]
	v_add_f32_e32 v34, v34, v35
	v_add_f32_e32 v34, v36, v34
	v_pk_mul_f32 v[38:39], v[70:71], v[70:71]
	v_add_f32_e32 v34, v37, v34
	v_add_f32_e32 v34, v38, v34
	v_pk_mul_f32 v[40:41], v[74:75], v[74:75]
	v_add_f32_e32 v34, v39, v34
	v_add_f32_e32 v34, v40, v34
	v_pk_mul_f32 v[42:43], v[72:73], v[72:73]
	v_add_f32_e32 v34, v41, v34
	v_add_f32_e32 v34, v42, v34
	v_pk_mul_f32 v[44:45], v[76:77], v[76:77]
	v_add_f32_e32 v34, v43, v34
	v_add_f32_e32 v34, v44, v34
	v_pk_mul_f32 v[46:47], v[32:33], v[32:33]
	v_add_f32_e32 v34, v45, v34
	v_add_f32_e32 v34, v46, v34
	v_pk_mul_f32 v[80:81], v[78:79], v[78:79]
	v_add_f32_e32 v34, v47, v34
	v_add_f32_e32 v34, v80, v34
	v_add_f32_e32 v34, v81, v34
	ds_bpermute_b32 v35, v220, v34
	s_waitcnt lgkmcnt(0)
	v_add_f32_e32 v34, v34, v35
	ds_bpermute_b32 v35, v221, v34
	s_waitcnt lgkmcnt(0)
	v_add_f32_e32 v34, v34, v35
	v_fmamk_f32 v34, v34, 0x3c800000, v166
	v_mul_f32_e32 v35, 0x4b800000, v34
	v_cmp_gt_f32_e32 vcc, s12, v34
	s_nop 1
	v_cndmask_b32_e32 v34, v34, v35, vcc
	v_rsq_f32_e32 v34, v34
	s_nop 0
	v_mul_f32_e32 v35, 0x45800000, v34
	v_cndmask_b32_e32 v34, v34, v35, vcc
	v_mul_f32_e32 v80, v197, v34
	s_nop 0
	v_pk_mul_f32 v[38:39], v[48:49], v[80:81] op_sel_hi:[1,0]
	s_nop 0
	v_pk_mul_f32 v[46:47], v[52:53], v[80:81] op_sel_hi:[1,0]
	v_pk_mul_f32 v[40:41], v[70:71], v[38:39]
	v_pk_mul_f32 v[38:39], v[50:51], v[80:81] op_sel_hi:[1,0]
	v_pk_mul_f32 v[34:35], v[56:57], v[80:81] op_sel_hi:[1,0]
	v_pk_mul_f32 v[36:37], v[58:59], v[80:81] op_sel_hi:[1,0]
	v_pk_mul_f32 v[44:45], v[74:75], v[38:39]
	s_nop 0
	v_pk_mul_f32 v[38:39], v[60:61], v[80:81] op_sel_hi:[1,0]
	v_pk_mul_f32 v[42:43], v[62:63], v[80:81] op_sel_hi:[1,0]
	v_pk_mul_f32 v[46:47], v[32:33], v[46:47]
	v_pk_mul_f32 v[32:33], v[54:55], v[80:81] op_sel_hi:[1,0]
	v_pk_mul_f32 v[34:35], v[66:67], v[34:35]
	v_pk_mul_f32 v[36:37], v[68:69], v[36:37]
	v_pk_mul_f32 v[38:39], v[72:73], v[38:39]
	v_pk_mul_f32 v[42:43], v[76:77], v[42:43]
	v_pk_mul_f32 v[80:81], v[78:79], v[32:33]
	s_and_b64 vcc, exec, s[4:5]
	s_cbranch_vccz .LBB0_243

.LBB0_272:
	v_pk_mul_f32 v[16:17], v[28:29], v[28:29]
	v_pk_mul_f32 v[18:19], v[34:35], v[34:35]
	v_add_f32_e32 v16, v16, v17
	v_add_f32_e32 v16, v18, v16
	v_pk_mul_f32 v[20:21], v[36:37], v[36:37]
	v_add_f32_e32 v16, v19, v16
	v_add_f32_e32 v16, v20, v16
	v_pk_mul_f32 v[22:23], v[42:43], v[42:43]
	v_add_f32_e32 v16, v21, v16
	v_add_f32_e32 v16, v22, v16
	v_pk_mul_f32 v[24:25], v[38:39], v[38:39]
	v_add_f32_e32 v16, v23, v16
	v_add_f32_e32 v16, v24, v16
	v_pk_mul_f32 v[26:27], v[44:45], v[44:45]
	v_add_f32_e32 v16, v25, v16
	v_add_f32_e32 v16, v26, v16
	v_pk_mul_f32 v[30:31], v[40:41], v[40:41]
	v_add_f32_e32 v16, v27, v16
	v_add_f32_e32 v16, v30, v16
	v_pk_mul_f32 v[66:67], v[46:47], v[46:47]
	v_add_f32_e32 v16, v31, v16
	v_add_f32_e32 v16, v66, v16
	v_add_f32_e32 v16, v67, v16
	ds_bpermute_b32 v17, v220, v16
	s_waitcnt lgkmcnt(0)
	v_add_f32_e32 v16, v16, v17
	ds_bpermute_b32 v17, v221, v16
	s_waitcnt lgkmcnt(0)
	v_add_f32_e32 v16, v16, v17
	v_fmamk_f32 v16, v16, 0x3c800000, v166
	v_mul_f32_e32 v17, 0x4b800000, v16
	v_cmp_gt_f32_e32 vcc, s12, v16
	s_nop 1
	v_cndmask_b32_e32 v16, v16, v17, vcc
	v_rsq_f32_e32 v16, v16
	s_nop 0
	v_mul_f32_e32 v17, 0x45800000, v16
	v_cndmask_b32_e32 v16, v16, v17, vcc
	v_mul_f32_e32 v66, v197, v16
	s_nop 0
	v_pk_mul_f32 v[16:17], v[56:57], v[66:67] op_sel_hi:[1,0]
	v_pk_mul_f32 v[20:21], v[48:49], v[66:67] op_sel_hi:[1,0]
	v_pk_mul_f32 v[16:17], v[28:29], v[16:17]
	v_pk_mul_f32 v[22:23], v[36:37], v[20:21]
	v_pk_mul_f32 v[20:21], v[50:51], v[66:67] op_sel_hi:[1,0]
	s_nop 0
	v_pk_mul_f32 v[28:29], v[52:53], v[66:67] op_sel_hi:[1,0]
	v_pk_mul_f32 v[18:19], v[58:59], v[66:67] op_sel_hi:[1,0]
	v_pk_mul_f32 v[26:27], v[42:43], v[20:21]
	s_nop 0
	v_pk_mul_f32 v[20:21], v[60:61], v[66:67] op_sel_hi:[1,0]
	v_pk_mul_f32 v[24:25], v[62:63], v[66:67] op_sel_hi:[1,0]
	v_pk_mul_f32 v[30:31], v[40:41], v[28:29]
	v_pk_mul_f32 v[28:29], v[54:55], v[66:67] op_sel_hi:[1,0]
	v_pk_mul_f32 v[18:19], v[34:35], v[18:19]
	v_pk_mul_f32 v[20:21], v[38:39], v[20:21]
	v_pk_mul_f32 v[24:25], v[44:45], v[24:25]
	v_pk_mul_f32 v[66:67], v[46:47], v[28:29]
	s_and_b64 vcc, exec, s[4:5]
	s_cbranch_vccz .LBB0_260

.LBB0_289:
	v_pk_mul_f32 v[0:1], v[12:13], v[12:13]
	v_pk_mul_f32 v[2:3], v[14:15], v[14:15]
	v_add_f32_e32 v0, v0, v1
	v_add_f32_e32 v0, v2, v0
	v_pk_mul_f32 v[4:5], v[16:17], v[16:17]
	v_add_f32_e32 v0, v3, v0
	v_add_f32_e32 v0, v4, v0
	v_pk_mul_f32 v[6:7], v[22:23], v[22:23]
	v_add_f32_e32 v0, v5, v0
	v_add_f32_e32 v0, v6, v0
	v_pk_mul_f32 v[8:9], v[18:19], v[18:19]
	v_add_f32_e32 v0, v7, v0
	v_add_f32_e32 v0, v8, v0
	v_pk_mul_f32 v[10:11], v[24:25], v[24:25]
	v_add_f32_e32 v0, v9, v0
	v_add_f32_e32 v0, v10, v0
	v_pk_mul_f32 v[28:29], v[20:21], v[20:21]
	v_add_f32_e32 v0, v11, v0
	v_add_f32_e32 v0, v28, v0
	v_pk_mul_f32 v[30:31], v[26:27], v[26:27]
	v_add_f32_e32 v0, v29, v0
	v_add_f32_e32 v0, v30, v0
	v_add_f32_e32 v0, v31, v0
	ds_bpermute_b32 v1, v220, v0
	s_waitcnt lgkmcnt(0)
	v_add_f32_e32 v0, v0, v1
	ds_bpermute_b32 v1, v221, v0
	s_waitcnt lgkmcnt(0)
	v_add_f32_e32 v0, v0, v1
	v_fmamk_f32 v0, v0, 0x3c800000, v166
	v_mul_f32_e32 v1, 0x4b800000, v0
	v_cmp_gt_f32_e32 vcc, s12, v0
	s_nop 1
	v_cndmask_b32_e32 v0, v0, v1, vcc
	v_rsq_f32_e32 v0, v0
	s_nop 0
	v_mul_f32_e32 v1, 0x45800000, v0
	v_cndmask_b32_e32 v0, v0, v1, vcc
	v_mul_f32_e32 v30, v197, v0
	s_nop 0
	v_pk_mul_f32 v[0:1], v[56:57], v[30:31] op_sel_hi:[1,0]
	v_pk_mul_f32 v[4:5], v[48:49], v[30:31] op_sel_hi:[1,0]
	v_pk_mul_f32 v[0:1], v[12:13], v[0:1]
	v_pk_mul_f32 v[6:7], v[16:17], v[4:5]
	v_pk_mul_f32 v[4:5], v[50:51], v[30:31] op_sel_hi:[1,0]
	s_nop 0
	v_pk_mul_f32 v[12:13], v[52:53], v[30:31] op_sel_hi:[1,0]
	v_pk_mul_f32 v[2:3], v[58:59], v[30:31] op_sel_hi:[1,0]
	v_pk_mul_f32 v[10:11], v[22:23], v[4:5]
	s_nop 0
	v_pk_mul_f32 v[4:5], v[60:61], v[30:31] op_sel_hi:[1,0]
	v_pk_mul_f32 v[8:9], v[62:63], v[30:31] op_sel_hi:[1,0]
	v_pk_mul_f32 v[28:29], v[20:21], v[12:13]
	v_pk_mul_f32 v[12:13], v[54:55], v[30:31] op_sel_hi:[1,0]
	v_pk_mul_f32 v[2:3], v[14:15], v[2:3]
	v_pk_mul_f32 v[4:5], v[18:19], v[4:5]
	v_pk_mul_f32 v[8:9], v[24:25], v[8:9]
	v_pk_mul_f32 v[30:31], v[26:27], v[12:13]
	s_and_b64 vcc, exec, s[4:5]
	s_cbranch_vccz .LBB0_277
